# T3: triangular-inverse off-diagonal block products (X=L21*T11, T21=-T22*X) on the f32 matrix core v_mfma_f32_32x32x2_f32 instead of VALU pk_fma
# speedup vs baseline: 1.0134x; 1.0134x over previous
.LBB0_281:
.LBB0_282:
	s_andn2_saveexec_b64 s[44:45], s[2:3]
	s_cbranch_execz .LBB0_296
	v_cndmask_b32_e64 v194, v244, v245, s[38:39]
	v_mov_b32_e32 v200, 0
	v_mov_b32_e32 v201, 0
	v_mov_b32_e32 v203, 0
	v_mul_u32_u24_e32 v204, 0x2280, v189
	v_add_u32_e32 v195, v194, v204
	v_mul_u32_u24_e32 v204, 0x1100, v189
	v_add_u32_e32 v204, 0x2200, v204
	v_add_u32_e32 v196, v194, v204
	s_cmp_lg_u32 s87, 0
	s_cselect_b32 s0, 0x2000, 0
	s_add_u32 s0, s0, 0x1e800
	v_lshlrev_b32_e32 v199, 2, v188
	v_lshl_add_u32 v197, v189, 11, s0
	v_sub_u32_e32 v204, 1, v189
	v_lshl_add_u32 v204, v204, 12, s0
	v_add_u32_e32 v198, v204, v199
	ds_read_b128 v[80:83], v195 offset:272
	v_cmp_eq_u32_e32 vcc, 0, v188
	s_nop 1
	v_cndmask_b32_e64 v0, 0, 1.0, vcc
	v_cmp_eq_u32_e32 vcc, 1, v188
	s_nop 1
	v_cndmask_b32_e64 v202, 0, 1.0, vcc
	s_waitcnt lgkmcnt(0)
	v_fma_f32 v146, -v0, v80, v202
	ds_read_b128 v[80:83], v195 offset:544
	v_mov_b32_e32 v1, v146
	v_cmp_eq_u32_e32 vcc, 2, v188
	s_nop 1
	v_cndmask_b32_e64 v202, 0, 1.0, vcc
	s_waitcnt lgkmcnt(0)
	v_pk_fma_f32 v[146:147], v[0:1], v[80:81], v[202:203] neg_lo:[1,0,0] neg_hi:[1,0,0]
	ds_read_b128 v[80:83], v195 offset:816
	v_add_f32_e32 v2, v146, v147
	v_cmp_eq_u32_e32 vcc, 3, v188
	s_nop 1
	v_cndmask_b32_e64 v202, 0, 1.0, vcc
	s_waitcnt lgkmcnt(0)
	v_pk_fma_f32 v[146:147], v[0:1], v[80:81], v[202:203] neg_lo:[1,0,0] neg_hi:[1,0,0]
	v_fma_f32 v148, -v2, v82, v200
	ds_read_b128 v[80:83], v195 offset:1088
	v_add_f32_e32 v150, v146, v147
	v_add_f32_e32 v3, v148, v150
	v_cmp_eq_u32_e32 vcc, 4, v188
	s_nop 1
	v_cndmask_b32_e64 v202, 0, 1.0, vcc
	s_waitcnt lgkmcnt(0)
	v_pk_fma_f32 v[146:147], v[0:1], v[80:81], v[202:203] neg_lo:[1,0,0] neg_hi:[1,0,0]
	v_pk_fma_f32 v[148:149], v[2:3], v[82:83], v[200:201] neg_lo:[1,0,0] neg_hi:[1,0,0]
	ds_read_b128 v[80:83], v195 offset:1360
	ds_read_b128 v[84:87], v195 offset:1376
	v_add_f32_e32 v150, v147, v146
	v_add_f32_e32 v151, v148, v149
	v_add_f32_e32 v4, v151, v150
	v_cmp_eq_u32_e32 vcc, 5, v188
	s_nop 1
	v_cndmask_b32_e64 v202, 0, 1.0, vcc
	s_waitcnt lgkmcnt(0)
	v_pk_fma_f32 v[146:147], v[0:1], v[80:81], v[202:203] neg_lo:[1,0,0] neg_hi:[1,0,0]
	v_pk_fma_f32 v[148:149], v[2:3], v[82:83], v[200:201] neg_lo:[1,0,0] neg_hi:[1,0,0]
	ds_read_b128 v[80:83], v195 offset:1632
	v_fma_f32 v146, -v4, v84, v146
	ds_read_b128 v[84:87], v195 offset:1648
	v_add_f32_e32 v150, v147, v146
	v_add_f32_e32 v151, v148, v149
	v_add_f32_e32 v5, v151, v150
	v_cmp_eq_u32_e32 vcc, 6, v188
	s_nop 1
	v_cndmask_b32_e64 v202, 0, 1.0, vcc
	s_waitcnt lgkmcnt(0)
	v_pk_fma_f32 v[146:147], v[0:1], v[80:81], v[202:203] neg_lo:[1,0,0] neg_hi:[1,0,0]
	v_pk_fma_f32 v[148:149], v[2:3], v[82:83], v[200:201] neg_lo:[1,0,0] neg_hi:[1,0,0]
	ds_read_b128 v[80:83], v195 offset:1904
	v_pk_fma_f32 v[146:147], v[4:5], v[84:85], v[146:147] neg_lo:[1,0,0] neg_hi:[1,0,0]
	ds_read_b128 v[84:87], v195 offset:1920
	v_add_f32_e32 v150, v147, v146
	v_add_f32_e32 v151, v148, v149
	v_add_f32_e32 v6, v151, v150
	v_cmp_eq_u32_e32 vcc, 7, v188
	s_nop 1
	v_cndmask_b32_e64 v202, 0, 1.0, vcc
	s_waitcnt lgkmcnt(0)
	v_pk_fma_f32 v[146:147], v[0:1], v[80:81], v[202:203] neg_lo:[1,0,0] neg_hi:[1,0,0]
	v_pk_fma_f32 v[148:149], v[2:3], v[82:83], v[200:201] neg_lo:[1,0,0] neg_hi:[1,0,0]
	ds_read_b128 v[80:83], v195 offset:2176
	v_pk_fma_f32 v[146:147], v[4:5], v[84:85], v[146:147] neg_lo:[1,0,0] neg_hi:[1,0,0]
	v_fma_f32 v148, -v6, v86, v148
	ds_read_b128 v[84:87], v195 offset:2192
	v_add_f32_e32 v150, v147, v146
	v_add_f32_e32 v151, v148, v149
	v_add_f32_e32 v7, v151, v150
	v_cmp_eq_u32_e32 vcc, 8, v188
	s_nop 1
	v_cndmask_b32_e64 v202, 0, 1.0, vcc
	s_waitcnt lgkmcnt(0)
	v_pk_fma_f32 v[146:147], v[0:1], v[80:81], v[202:203] neg_lo:[1,0,0] neg_hi:[1,0,0]
	v_pk_fma_f32 v[148:149], v[2:3], v[82:83], v[200:201] neg_lo:[1,0,0] neg_hi:[1,0,0]
	ds_read_b128 v[80:83], v195 offset:2448
	v_pk_fma_f32 v[146:147], v[4:5], v[84:85], v[146:147] neg_lo:[1,0,0] neg_hi:[1,0,0]
	v_pk_fma_f32 v[148:149], v[6:7], v[86:87], v[148:149] neg_lo:[1,0,0] neg_hi:[1,0,0]
	ds_read_b128 v[84:87], v195 offset:2464
	ds_read_b128 v[88:91], v195 offset:2480
	v_add_f32_e32 v150, v147, v146
	v_add_f32_e32 v151, v148, v149
	v_add_f32_e32 v8, v151, v150
	v_cmp_eq_u32_e32 vcc, 9, v188
	s_nop 1
	v_cndmask_b32_e64 v202, 0, 1.0, vcc
	s_waitcnt lgkmcnt(0)
	v_pk_fma_f32 v[146:147], v[0:1], v[80:81], v[202:203] neg_lo:[1,0,0] neg_hi:[1,0,0]
	v_pk_fma_f32 v[148:149], v[2:3], v[82:83], v[200:201] neg_lo:[1,0,0] neg_hi:[1,0,0]
	ds_read_b128 v[80:83], v195 offset:2720
	v_pk_fma_f32 v[146:147], v[4:5], v[84:85], v[146:147] neg_lo:[1,0,0] neg_hi:[1,0,0]
	v_pk_fma_f32 v[148:149], v[6:7], v[86:87], v[148:149] neg_lo:[1,0,0] neg_hi:[1,0,0]
	ds_read_b128 v[84:87], v195 offset:2736
	v_fma_f32 v146, -v8, v88, v146
	ds_read_b128 v[88:91], v195 offset:2752
	v_add_f32_e32 v150, v147, v146
	v_add_f32_e32 v151, v148, v149
	v_add_f32_e32 v9, v151, v150
	v_cmp_eq_u32_e32 vcc, 10, v188
	s_nop 1
	v_cndmask_b32_e64 v202, 0, 1.0, vcc
	s_waitcnt lgkmcnt(0)
	v_pk_fma_f32 v[146:147], v[0:1], v[80:81], v[202:203] neg_lo:[1,0,0] neg_hi:[1,0,0]
	v_pk_fma_f32 v[148:149], v[2:3], v[82:83], v[200:201] neg_lo:[1,0,0] neg_hi:[1,0,0]
	ds_read_b128 v[80:83], v195 offset:2992
	v_pk_fma_f32 v[146:147], v[4:5], v[84:85], v[146:147] neg_lo:[1,0,0] neg_hi:[1,0,0]
	v_pk_fma_f32 v[148:149], v[6:7], v[86:87], v[148:149] neg_lo:[1,0,0] neg_hi:[1,0,0]
	ds_read_b128 v[84:87], v195 offset:3008
	v_pk_fma_f32 v[146:147], v[8:9], v[88:89], v[146:147] neg_lo:[1,0,0] neg_hi:[1,0,0]
	ds_read_b128 v[88:91], v195 offset:3024
	v_add_f32_e32 v150, v147, v146
	v_add_f32_e32 v151, v148, v149
	v_add_f32_e32 v10, v151, v150
	v_cmp_eq_u32_e32 vcc, 11, v188
	s_nop 1
	v_cndmask_b32_e64 v202, 0, 1.0, vcc
	s_waitcnt lgkmcnt(0)
	v_pk_fma_f32 v[146:147], v[0:1], v[80:81], v[202:203] neg_lo:[1,0,0] neg_hi:[1,0,0]
	v_pk_fma_f32 v[148:149], v[2:3], v[82:83], v[200:201] neg_lo:[1,0,0] neg_hi:[1,0,0]
	ds_read_b128 v[80:83], v195 offset:3264
	v_pk_fma_f32 v[146:147], v[4:5], v[84:85], v[146:147] neg_lo:[1,0,0] neg_hi:[1,0,0]
	v_pk_fma_f32 v[148:149], v[6:7], v[86:87], v[148:149] neg_lo:[1,0,0] neg_hi:[1,0,0]
	ds_read_b128 v[84:87], v195 offset:3280
	v_pk_fma_f32 v[146:147], v[8:9], v[88:89], v[146:147] neg_lo:[1,0,0] neg_hi:[1,0,0]
	v_fma_f32 v148, -v10, v90, v148
	ds_read_b128 v[88:91], v195 offset:3296
	v_add_f32_e32 v150, v147, v146
	v_add_f32_e32 v151, v148, v149
	v_add_f32_e32 v11, v151, v150
	v_cmp_eq_u32_e32 vcc, 12, v188
	s_nop 1
	v_cndmask_b32_e64 v202, 0, 1.0, vcc
	s_waitcnt lgkmcnt(0)
	v_pk_fma_f32 v[146:147], v[0:1], v[80:81], v[202:203] neg_lo:[1,0,0] neg_hi:[1,0,0]
	v_pk_fma_f32 v[148:149], v[2:3], v[82:83], v[200:201] neg_lo:[1,0,0] neg_hi:[1,0,0]
	ds_read_b128 v[80:83], v195 offset:3536
	v_pk_fma_f32 v[146:147], v[4:5], v[84:85], v[146:147] neg_lo:[1,0,0] neg_hi:[1,0,0]
	v_pk_fma_f32 v[148:149], v[6:7], v[86:87], v[148:149] neg_lo:[1,0,0] neg_hi:[1,0,0]
	ds_read_b128 v[84:87], v195 offset:3552
	v_pk_fma_f32 v[146:147], v[8:9], v[88:89], v[146:147] neg_lo:[1,0,0] neg_hi:[1,0,0]
	v_pk_fma_f32 v[148:149], v[10:11], v[90:91], v[148:149] neg_lo:[1,0,0] neg_hi:[1,0,0]
	ds_read_b128 v[88:91], v195 offset:3568
	ds_read_b128 v[92:95], v195 offset:3584
	v_add_f32_e32 v150, v147, v146
	v_add_f32_e32 v151, v148, v149
	v_add_f32_e32 v12, v151, v150
	v_cmp_eq_u32_e32 vcc, 13, v188
	s_nop 1
	v_cndmask_b32_e64 v202, 0, 1.0, vcc
	s_waitcnt lgkmcnt(0)
	v_pk_fma_f32 v[146:147], v[0:1], v[80:81], v[202:203] neg_lo:[1,0,0] neg_hi:[1,0,0]
	v_pk_fma_f32 v[148:149], v[2:3], v[82:83], v[200:201] neg_lo:[1,0,0] neg_hi:[1,0,0]
	ds_read_b128 v[80:83], v195 offset:3808
	v_pk_fma_f32 v[146:147], v[4:5], v[84:85], v[146:147] neg_lo:[1,0,0] neg_hi:[1,0,0]
	v_pk_fma_f32 v[148:149], v[6:7], v[86:87], v[148:149] neg_lo:[1,0,0] neg_hi:[1,0,0]
	ds_read_b128 v[84:87], v195 offset:3824
	v_pk_fma_f32 v[146:147], v[8:9], v[88:89], v[146:147] neg_lo:[1,0,0] neg_hi:[1,0,0]
	v_pk_fma_f32 v[148:149], v[10:11], v[90:91], v[148:149] neg_lo:[1,0,0] neg_hi:[1,0,0]
	ds_read_b128 v[88:91], v195 offset:3840
	v_fma_f32 v146, -v12, v92, v146
	ds_read_b128 v[92:95], v195 offset:3856
	v_add_f32_e32 v150, v147, v146
	v_add_f32_e32 v151, v148, v149
	v_add_f32_e32 v13, v151, v150
	v_cmp_eq_u32_e32 vcc, 14, v188
	s_nop 1
	v_cndmask_b32_e64 v202, 0, 1.0, vcc
	s_waitcnt lgkmcnt(0)
	v_pk_fma_f32 v[146:147], v[0:1], v[80:81], v[202:203] neg_lo:[1,0,0] neg_hi:[1,0,0]
	v_pk_fma_f32 v[148:149], v[2:3], v[82:83], v[200:201] neg_lo:[1,0,0] neg_hi:[1,0,0]
	ds_read_b128 v[80:83], v195 offset:4080
	v_pk_fma_f32 v[146:147], v[4:5], v[84:85], v[146:147] neg_lo:[1,0,0] neg_hi:[1,0,0]
	v_pk_fma_f32 v[148:149], v[6:7], v[86:87], v[148:149] neg_lo:[1,0,0] neg_hi:[1,0,0]
	ds_read_b128 v[84:87], v195 offset:4096
	v_pk_fma_f32 v[146:147], v[8:9], v[88:89], v[146:147] neg_lo:[1,0,0] neg_hi:[1,0,0]
	v_pk_fma_f32 v[148:149], v[10:11], v[90:91], v[148:149] neg_lo:[1,0,0] neg_hi:[1,0,0]
	ds_read_b128 v[88:91], v195 offset:4112
	v_pk_fma_f32 v[146:147], v[12:13], v[92:93], v[146:147] neg_lo:[1,0,0] neg_hi:[1,0,0]
	ds_read_b128 v[92:95], v195 offset:4128
	v_add_f32_e32 v150, v147, v146
	v_add_f32_e32 v151, v148, v149
	v_add_f32_e32 v14, v151, v150
	v_cmp_eq_u32_e32 vcc, 15, v188
	s_nop 1
	v_cndmask_b32_e64 v202, 0, 1.0, vcc
	s_waitcnt lgkmcnt(0)
	v_pk_fma_f32 v[146:147], v[0:1], v[80:81], v[202:203] neg_lo:[1,0,0] neg_hi:[1,0,0]
	v_pk_fma_f32 v[148:149], v[2:3], v[82:83], v[200:201] neg_lo:[1,0,0] neg_hi:[1,0,0]
	ds_read_b128 v[80:83], v195 offset:4352
	v_pk_fma_f32 v[146:147], v[4:5], v[84:85], v[146:147] neg_lo:[1,0,0] neg_hi:[1,0,0]
	v_pk_fma_f32 v[148:149], v[6:7], v[86:87], v[148:149] neg_lo:[1,0,0] neg_hi:[1,0,0]
	ds_read_b128 v[84:87], v195 offset:4368
	v_pk_fma_f32 v[146:147], v[8:9], v[88:89], v[146:147] neg_lo:[1,0,0] neg_hi:[1,0,0]
	v_pk_fma_f32 v[148:149], v[10:11], v[90:91], v[148:149] neg_lo:[1,0,0] neg_hi:[1,0,0]
	ds_read_b128 v[88:91], v195 offset:4384
	v_pk_fma_f32 v[146:147], v[12:13], v[92:93], v[146:147] neg_lo:[1,0,0] neg_hi:[1,0,0]
	v_fma_f32 v148, -v14, v94, v148
	ds_read_b128 v[92:95], v195 offset:4400
	v_add_f32_e32 v150, v147, v146
	v_add_f32_e32 v151, v148, v149
	v_add_f32_e32 v15, v151, v150
	v_cmp_eq_u32_e32 vcc, 16, v188
	s_nop 1
	v_cndmask_b32_e64 v202, 0, 1.0, vcc
	s_waitcnt lgkmcnt(0)
	v_pk_fma_f32 v[146:147], v[0:1], v[80:81], v[202:203] neg_lo:[1,0,0] neg_hi:[1,0,0]
	v_pk_fma_f32 v[148:149], v[2:3], v[82:83], v[200:201] neg_lo:[1,0,0] neg_hi:[1,0,0]
	ds_read_b128 v[80:83], v195 offset:4624
	v_pk_fma_f32 v[146:147], v[4:5], v[84:85], v[146:147] neg_lo:[1,0,0] neg_hi:[1,0,0]
	v_pk_fma_f32 v[148:149], v[6:7], v[86:87], v[148:149] neg_lo:[1,0,0] neg_hi:[1,0,0]
	ds_read_b128 v[84:87], v195 offset:4640
	v_pk_fma_f32 v[146:147], v[8:9], v[88:89], v[146:147] neg_lo:[1,0,0] neg_hi:[1,0,0]
	v_pk_fma_f32 v[148:149], v[10:11], v[90:91], v[148:149] neg_lo:[1,0,0] neg_hi:[1,0,0]
	ds_read_b128 v[88:91], v195 offset:4656
	v_pk_fma_f32 v[146:147], v[12:13], v[92:93], v[146:147] neg_lo:[1,0,0] neg_hi:[1,0,0]
	v_pk_fma_f32 v[148:149], v[14:15], v[94:95], v[148:149] neg_lo:[1,0,0] neg_hi:[1,0,0]
	ds_read_b128 v[92:95], v195 offset:4672
	ds_read_b128 v[96:99], v195 offset:4688
	v_add_f32_e32 v150, v147, v146
	v_add_f32_e32 v151, v148, v149
	v_add_f32_e32 v16, v151, v150
	v_cmp_eq_u32_e32 vcc, 17, v188
	s_nop 1
	v_cndmask_b32_e64 v202, 0, 1.0, vcc
	s_waitcnt lgkmcnt(1)
	v_pk_fma_f32 v[146:147], v[0:1], v[80:81], v[202:203] neg_lo:[1,0,0] neg_hi:[1,0,0]
	v_pk_fma_f32 v[148:149], v[2:3], v[82:83], v[200:201] neg_lo:[1,0,0] neg_hi:[1,0,0]
	ds_read_b128 v[80:83], v195 offset:4896
	v_pk_fma_f32 v[146:147], v[4:5], v[84:85], v[146:147] neg_lo:[1,0,0] neg_hi:[1,0,0]
	v_pk_fma_f32 v[148:149], v[6:7], v[86:87], v[148:149] neg_lo:[1,0,0] neg_hi:[1,0,0]
	ds_read_b128 v[84:87], v195 offset:4912
	v_pk_fma_f32 v[146:147], v[8:9], v[88:89], v[146:147] neg_lo:[1,0,0] neg_hi:[1,0,0]
	v_pk_fma_f32 v[148:149], v[10:11], v[90:91], v[148:149] neg_lo:[1,0,0] neg_hi:[1,0,0]
	ds_read_b128 v[88:91], v195 offset:4928
	v_pk_fma_f32 v[146:147], v[12:13], v[92:93], v[146:147] neg_lo:[1,0,0] neg_hi:[1,0,0]
	v_pk_fma_f32 v[148:149], v[14:15], v[94:95], v[148:149] neg_lo:[1,0,0] neg_hi:[1,0,0]
	ds_read_b128 v[92:95], v195 offset:4944
	s_waitcnt lgkmcnt(4)
	v_fma_f32 v146, -v16, v96, v146
	ds_read_b128 v[96:99], v195 offset:4960
	v_add_f32_e32 v150, v147, v146
	v_add_f32_e32 v151, v148, v149
	v_add_f32_e32 v17, v151, v150
	v_cmp_eq_u32_e32 vcc, 18, v188
	s_nop 1
	v_cndmask_b32_e64 v202, 0, 1.0, vcc
	s_waitcnt lgkmcnt(1)
	v_pk_fma_f32 v[146:147], v[0:1], v[80:81], v[202:203] neg_lo:[1,0,0] neg_hi:[1,0,0]
	v_pk_fma_f32 v[148:149], v[2:3], v[82:83], v[200:201] neg_lo:[1,0,0] neg_hi:[1,0,0]
	ds_read_b128 v[80:83], v195 offset:5168
	v_pk_fma_f32 v[146:147], v[4:5], v[84:85], v[146:147] neg_lo:[1,0,0] neg_hi:[1,0,0]
	v_pk_fma_f32 v[148:149], v[6:7], v[86:87], v[148:149] neg_lo:[1,0,0] neg_hi:[1,0,0]
	ds_read_b128 v[84:87], v195 offset:5184
	v_pk_fma_f32 v[146:147], v[8:9], v[88:89], v[146:147] neg_lo:[1,0,0] neg_hi:[1,0,0]
	v_pk_fma_f32 v[148:149], v[10:11], v[90:91], v[148:149] neg_lo:[1,0,0] neg_hi:[1,0,0]
	ds_read_b128 v[88:91], v195 offset:5200
	v_pk_fma_f32 v[146:147], v[12:13], v[92:93], v[146:147] neg_lo:[1,0,0] neg_hi:[1,0,0]
	v_pk_fma_f32 v[148:149], v[14:15], v[94:95], v[148:149] neg_lo:[1,0,0] neg_hi:[1,0,0]
	ds_read_b128 v[92:95], v195 offset:5216
	s_waitcnt lgkmcnt(4)
	v_pk_fma_f32 v[146:147], v[16:17], v[96:97], v[146:147] neg_lo:[1,0,0] neg_hi:[1,0,0]
	ds_read_b128 v[96:99], v195 offset:5232
	v_add_f32_e32 v150, v147, v146
	v_add_f32_e32 v151, v148, v149
	v_add_f32_e32 v18, v151, v150
	v_cmp_eq_u32_e32 vcc, 19, v188
	s_nop 1
	v_cndmask_b32_e64 v202, 0, 1.0, vcc
	s_waitcnt lgkmcnt(1)
	v_pk_fma_f32 v[146:147], v[0:1], v[80:81], v[202:203] neg_lo:[1,0,0] neg_hi:[1,0,0]
	v_pk_fma_f32 v[148:149], v[2:3], v[82:83], v[200:201] neg_lo:[1,0,0] neg_hi:[1,0,0]
	ds_read_b128 v[80:83], v195 offset:5440
	v_pk_fma_f32 v[146:147], v[4:5], v[84:85], v[146:147] neg_lo:[1,0,0] neg_hi:[1,0,0]
	v_pk_fma_f32 v[148:149], v[6:7], v[86:87], v[148:149] neg_lo:[1,0,0] neg_hi:[1,0,0]
	ds_read_b128 v[84:87], v195 offset:5456
	v_pk_fma_f32 v[146:147], v[8:9], v[88:89], v[146:147] neg_lo:[1,0,0] neg_hi:[1,0,0]
	v_pk_fma_f32 v[148:149], v[10:11], v[90:91], v[148:149] neg_lo:[1,0,0] neg_hi:[1,0,0]
	ds_read_b128 v[88:91], v195 offset:5472
	v_pk_fma_f32 v[146:147], v[12:13], v[92:93], v[146:147] neg_lo:[1,0,0] neg_hi:[1,0,0]
	v_pk_fma_f32 v[148:149], v[14:15], v[94:95], v[148:149] neg_lo:[1,0,0] neg_hi:[1,0,0]
	ds_read_b128 v[92:95], v195 offset:5488
	s_waitcnt lgkmcnt(4)
	v_pk_fma_f32 v[146:147], v[16:17], v[96:97], v[146:147] neg_lo:[1,0,0] neg_hi:[1,0,0]
	v_fma_f32 v148, -v18, v98, v148
	ds_read_b128 v[96:99], v195 offset:5504
	v_add_f32_e32 v150, v147, v146
	v_add_f32_e32 v151, v148, v149
	v_add_f32_e32 v19, v151, v150
	v_cmp_eq_u32_e32 vcc, 20, v188
	s_nop 1
	v_cndmask_b32_e64 v202, 0, 1.0, vcc
	s_waitcnt lgkmcnt(1)
	v_pk_fma_f32 v[146:147], v[0:1], v[80:81], v[202:203] neg_lo:[1,0,0] neg_hi:[1,0,0]
	v_pk_fma_f32 v[148:149], v[2:3], v[82:83], v[200:201] neg_lo:[1,0,0] neg_hi:[1,0,0]
	ds_read_b128 v[80:83], v195 offset:5712
	v_pk_fma_f32 v[146:147], v[4:5], v[84:85], v[146:147] neg_lo:[1,0,0] neg_hi:[1,0,0]
	v_pk_fma_f32 v[148:149], v[6:7], v[86:87], v[148:149] neg_lo:[1,0,0] neg_hi:[1,0,0]
	ds_read_b128 v[84:87], v195 offset:5728
	v_pk_fma_f32 v[146:147], v[8:9], v[88:89], v[146:147] neg_lo:[1,0,0] neg_hi:[1,0,0]
	v_pk_fma_f32 v[148:149], v[10:11], v[90:91], v[148:149] neg_lo:[1,0,0] neg_hi:[1,0,0]
	ds_read_b128 v[88:91], v195 offset:5744
	v_pk_fma_f32 v[146:147], v[12:13], v[92:93], v[146:147] neg_lo:[1,0,0] neg_hi:[1,0,0]
	v_pk_fma_f32 v[148:149], v[14:15], v[94:95], v[148:149] neg_lo:[1,0,0] neg_hi:[1,0,0]
	ds_read_b128 v[92:95], v195 offset:5760
	s_waitcnt lgkmcnt(4)
	v_pk_fma_f32 v[146:147], v[16:17], v[96:97], v[146:147] neg_lo:[1,0,0] neg_hi:[1,0,0]
	v_pk_fma_f32 v[148:149], v[18:19], v[98:99], v[148:149] neg_lo:[1,0,0] neg_hi:[1,0,0]
	ds_read_b128 v[96:99], v195 offset:5776
	ds_read_b128 v[100:103], v195 offset:5792
	v_add_f32_e32 v150, v147, v146
	v_add_f32_e32 v151, v148, v149
	v_add_f32_e32 v20, v151, v150
	v_cmp_eq_u32_e32 vcc, 21, v188
	s_nop 1
	v_cndmask_b32_e64 v202, 0, 1.0, vcc
	s_waitcnt lgkmcnt(2)
	v_pk_fma_f32 v[146:147], v[0:1], v[80:81], v[202:203] neg_lo:[1,0,0] neg_hi:[1,0,0]
	v_pk_fma_f32 v[148:149], v[2:3], v[82:83], v[200:201] neg_lo:[1,0,0] neg_hi:[1,0,0]
	ds_read_b128 v[80:83], v195 offset:5984
	v_pk_fma_f32 v[146:147], v[4:5], v[84:85], v[146:147] neg_lo:[1,0,0] neg_hi:[1,0,0]
	v_pk_fma_f32 v[148:149], v[6:7], v[86:87], v[148:149] neg_lo:[1,0,0] neg_hi:[1,0,0]
	ds_read_b128 v[84:87], v195 offset:6000
	v_pk_fma_f32 v[146:147], v[8:9], v[88:89], v[146:147] neg_lo:[1,0,0] neg_hi:[1,0,0]
	v_pk_fma_f32 v[148:149], v[10:11], v[90:91], v[148:149] neg_lo:[1,0,0] neg_hi:[1,0,0]
	ds_read_b128 v[88:91], v195 offset:6016
	v_pk_fma_f32 v[146:147], v[12:13], v[92:93], v[146:147] neg_lo:[1,0,0] neg_hi:[1,0,0]
	v_pk_fma_f32 v[148:149], v[14:15], v[94:95], v[148:149] neg_lo:[1,0,0] neg_hi:[1,0,0]
	ds_read_b128 v[92:95], v195 offset:6032
	s_waitcnt lgkmcnt(4)
	v_pk_fma_f32 v[146:147], v[16:17], v[96:97], v[146:147] neg_lo:[1,0,0] neg_hi:[1,0,0]
	v_pk_fma_f32 v[148:149], v[18:19], v[98:99], v[148:149] neg_lo:[1,0,0] neg_hi:[1,0,0]
	ds_read_b128 v[96:99], v195 offset:6048
	v_fma_f32 v146, -v20, v100, v146
	ds_read_b128 v[100:103], v195 offset:6064
	v_add_f32_e32 v150, v147, v146
	v_add_f32_e32 v151, v148, v149
	v_add_f32_e32 v21, v151, v150
	v_cmp_eq_u32_e32 vcc, 22, v188
	s_nop 1
	v_cndmask_b32_e64 v202, 0, 1.0, vcc
	s_waitcnt lgkmcnt(2)
	v_pk_fma_f32 v[146:147], v[0:1], v[80:81], v[202:203] neg_lo:[1,0,0] neg_hi:[1,0,0]
	v_pk_fma_f32 v[148:149], v[2:3], v[82:83], v[200:201] neg_lo:[1,0,0] neg_hi:[1,0,0]
	ds_read_b128 v[80:83], v195 offset:6256
	v_pk_fma_f32 v[146:147], v[4:5], v[84:85], v[146:147] neg_lo:[1,0,0] neg_hi:[1,0,0]
	v_pk_fma_f32 v[148:149], v[6:7], v[86:87], v[148:149] neg_lo:[1,0,0] neg_hi:[1,0,0]
	ds_read_b128 v[84:87], v195 offset:6272
	v_pk_fma_f32 v[146:147], v[8:9], v[88:89], v[146:147] neg_lo:[1,0,0] neg_hi:[1,0,0]
	v_pk_fma_f32 v[148:149], v[10:11], v[90:91], v[148:149] neg_lo:[1,0,0] neg_hi:[1,0,0]
	ds_read_b128 v[88:91], v195 offset:6288
	v_pk_fma_f32 v[146:147], v[12:13], v[92:93], v[146:147] neg_lo:[1,0,0] neg_hi:[1,0,0]
	v_pk_fma_f32 v[148:149], v[14:15], v[94:95], v[148:149] neg_lo:[1,0,0] neg_hi:[1,0,0]
	ds_read_b128 v[92:95], v195 offset:6304
	s_waitcnt lgkmcnt(4)
	v_pk_fma_f32 v[146:147], v[16:17], v[96:97], v[146:147] neg_lo:[1,0,0] neg_hi:[1,0,0]
	v_pk_fma_f32 v[148:149], v[18:19], v[98:99], v[148:149] neg_lo:[1,0,0] neg_hi:[1,0,0]
	ds_read_b128 v[96:99], v195 offset:6320
	v_pk_fma_f32 v[146:147], v[20:21], v[100:101], v[146:147] neg_lo:[1,0,0] neg_hi:[1,0,0]
	ds_read_b128 v[100:103], v195 offset:6336
	v_add_f32_e32 v150, v147, v146
	v_add_f32_e32 v151, v148, v149
	v_add_f32_e32 v22, v151, v150
	v_cmp_eq_u32_e32 vcc, 23, v188
	s_nop 1
	v_cndmask_b32_e64 v202, 0, 1.0, vcc
	s_waitcnt lgkmcnt(2)
	v_pk_fma_f32 v[146:147], v[0:1], v[80:81], v[202:203] neg_lo:[1,0,0] neg_hi:[1,0,0]
	v_pk_fma_f32 v[148:149], v[2:3], v[82:83], v[200:201] neg_lo:[1,0,0] neg_hi:[1,0,0]
	ds_read_b128 v[80:83], v195 offset:6528
	v_pk_fma_f32 v[146:147], v[4:5], v[84:85], v[146:147] neg_lo:[1,0,0] neg_hi:[1,0,0]
	v_pk_fma_f32 v[148:149], v[6:7], v[86:87], v[148:149] neg_lo:[1,0,0] neg_hi:[1,0,0]
	ds_read_b128 v[84:87], v195 offset:6544
	v_pk_fma_f32 v[146:147], v[8:9], v[88:89], v[146:147] neg_lo:[1,0,0] neg_hi:[1,0,0]
	v_pk_fma_f32 v[148:149], v[10:11], v[90:91], v[148:149] neg_lo:[1,0,0] neg_hi:[1,0,0]
	ds_read_b128 v[88:91], v195 offset:6560
	v_pk_fma_f32 v[146:147], v[12:13], v[92:93], v[146:147] neg_lo:[1,0,0] neg_hi:[1,0,0]
	v_pk_fma_f32 v[148:149], v[14:15], v[94:95], v[148:149] neg_lo:[1,0,0] neg_hi:[1,0,0]
	ds_read_b128 v[92:95], v195 offset:6576
	s_waitcnt lgkmcnt(4)
	v_pk_fma_f32 v[146:147], v[16:17], v[96:97], v[146:147] neg_lo:[1,0,0] neg_hi:[1,0,0]
	v_pk_fma_f32 v[148:149], v[18:19], v[98:99], v[148:149] neg_lo:[1,0,0] neg_hi:[1,0,0]
	ds_read_b128 v[96:99], v195 offset:6592
	v_pk_fma_f32 v[146:147], v[20:21], v[100:101], v[146:147] neg_lo:[1,0,0] neg_hi:[1,0,0]
	v_fma_f32 v148, -v22, v102, v148
	ds_read_b128 v[100:103], v195 offset:6608
	v_add_f32_e32 v150, v147, v146
	v_add_f32_e32 v151, v148, v149
	v_add_f32_e32 v23, v151, v150
	v_cmp_eq_u32_e32 vcc, 24, v188
	s_nop 1
	v_cndmask_b32_e64 v202, 0, 1.0, vcc
	s_waitcnt lgkmcnt(2)
	v_pk_fma_f32 v[146:147], v[0:1], v[80:81], v[202:203] neg_lo:[1,0,0] neg_hi:[1,0,0]
	v_pk_fma_f32 v[148:149], v[2:3], v[82:83], v[200:201] neg_lo:[1,0,0] neg_hi:[1,0,0]
	ds_read_b128 v[80:83], v195 offset:6800
	v_pk_fma_f32 v[146:147], v[4:5], v[84:85], v[146:147] neg_lo:[1,0,0] neg_hi:[1,0,0]
	v_pk_fma_f32 v[148:149], v[6:7], v[86:87], v[148:149] neg_lo:[1,0,0] neg_hi:[1,0,0]
	ds_read_b128 v[84:87], v195 offset:6816
	v_pk_fma_f32 v[146:147], v[8:9], v[88:89], v[146:147] neg_lo:[1,0,0] neg_hi:[1,0,0]
	v_pk_fma_f32 v[148:149], v[10:11], v[90:91], v[148:149] neg_lo:[1,0,0] neg_hi:[1,0,0]
	ds_read_b128 v[88:91], v195 offset:6832
	v_pk_fma_f32 v[146:147], v[12:13], v[92:93], v[146:147] neg_lo:[1,0,0] neg_hi:[1,0,0]
	v_pk_fma_f32 v[148:149], v[14:15], v[94:95], v[148:149] neg_lo:[1,0,0] neg_hi:[1,0,0]
	ds_read_b128 v[92:95], v195 offset:6848
	s_waitcnt lgkmcnt(4)
	v_pk_fma_f32 v[146:147], v[16:17], v[96:97], v[146:147] neg_lo:[1,0,0] neg_hi:[1,0,0]
	v_pk_fma_f32 v[148:149], v[18:19], v[98:99], v[148:149] neg_lo:[1,0,0] neg_hi:[1,0,0]
	ds_read_b128 v[96:99], v195 offset:6864
	v_pk_fma_f32 v[146:147], v[20:21], v[100:101], v[146:147] neg_lo:[1,0,0] neg_hi:[1,0,0]
	v_pk_fma_f32 v[148:149], v[22:23], v[102:103], v[148:149] neg_lo:[1,0,0] neg_hi:[1,0,0]
	ds_read_b128 v[100:103], v195 offset:6880
	ds_read_b128 v[104:107], v195 offset:6896
	v_add_f32_e32 v150, v147, v146
	v_add_f32_e32 v151, v148, v149
	v_add_f32_e32 v24, v151, v150
	v_cmp_eq_u32_e32 vcc, 25, v188
	s_nop 1
	v_cndmask_b32_e64 v202, 0, 1.0, vcc
	s_waitcnt lgkmcnt(3)
	v_pk_fma_f32 v[146:147], v[0:1], v[80:81], v[202:203] neg_lo:[1,0,0] neg_hi:[1,0,0]
	v_pk_fma_f32 v[148:149], v[2:3], v[82:83], v[200:201] neg_lo:[1,0,0] neg_hi:[1,0,0]
	ds_read_b128 v[80:83], v195 offset:7072
	v_pk_fma_f32 v[146:147], v[4:5], v[84:85], v[146:147] neg_lo:[1,0,0] neg_hi:[1,0,0]
	v_pk_fma_f32 v[148:149], v[6:7], v[86:87], v[148:149] neg_lo:[1,0,0] neg_hi:[1,0,0]
	ds_read_b128 v[84:87], v195 offset:7088
	v_pk_fma_f32 v[146:147], v[8:9], v[88:89], v[146:147] neg_lo:[1,0,0] neg_hi:[1,0,0]
	v_pk_fma_f32 v[148:149], v[10:11], v[90:91], v[148:149] neg_lo:[1,0,0] neg_hi:[1,0,0]
	ds_read_b128 v[88:91], v195 offset:7104
	v_pk_fma_f32 v[146:147], v[12:13], v[92:93], v[146:147] neg_lo:[1,0,0] neg_hi:[1,0,0]
	v_pk_fma_f32 v[148:149], v[14:15], v[94:95], v[148:149] neg_lo:[1,0,0] neg_hi:[1,0,0]
	ds_read_b128 v[92:95], v195 offset:7120
	s_waitcnt lgkmcnt(4)
	v_pk_fma_f32 v[146:147], v[16:17], v[96:97], v[146:147] neg_lo:[1,0,0] neg_hi:[1,0,0]
	v_pk_fma_f32 v[148:149], v[18:19], v[98:99], v[148:149] neg_lo:[1,0,0] neg_hi:[1,0,0]
	ds_read_b128 v[96:99], v195 offset:7136
	v_pk_fma_f32 v[146:147], v[20:21], v[100:101], v[146:147] neg_lo:[1,0,0] neg_hi:[1,0,0]
	v_pk_fma_f32 v[148:149], v[22:23], v[102:103], v[148:149] neg_lo:[1,0,0] neg_hi:[1,0,0]
	ds_read_b128 v[100:103], v195 offset:7152
	v_fma_f32 v146, -v24, v104, v146
	ds_read_b128 v[104:107], v195 offset:7168
	v_add_f32_e32 v150, v147, v146
	v_add_f32_e32 v151, v148, v149
	v_add_f32_e32 v25, v151, v150
	v_cmp_eq_u32_e32 vcc, 26, v188
	s_nop 1
	v_cndmask_b32_e64 v202, 0, 1.0, vcc
	s_waitcnt lgkmcnt(3)
	v_pk_fma_f32 v[146:147], v[0:1], v[80:81], v[202:203] neg_lo:[1,0,0] neg_hi:[1,0,0]
	v_pk_fma_f32 v[148:149], v[2:3], v[82:83], v[200:201] neg_lo:[1,0,0] neg_hi:[1,0,0]
	ds_read_b128 v[80:83], v195 offset:7344
	v_pk_fma_f32 v[146:147], v[4:5], v[84:85], v[146:147] neg_lo:[1,0,0] neg_hi:[1,0,0]
	v_pk_fma_f32 v[148:149], v[6:7], v[86:87], v[148:149] neg_lo:[1,0,0] neg_hi:[1,0,0]
	ds_read_b128 v[84:87], v195 offset:7360
	v_pk_fma_f32 v[146:147], v[8:9], v[88:89], v[146:147] neg_lo:[1,0,0] neg_hi:[1,0,0]
	v_pk_fma_f32 v[148:149], v[10:11], v[90:91], v[148:149] neg_lo:[1,0,0] neg_hi:[1,0,0]
	ds_read_b128 v[88:91], v195 offset:7376
	v_pk_fma_f32 v[146:147], v[12:13], v[92:93], v[146:147] neg_lo:[1,0,0] neg_hi:[1,0,0]
	v_pk_fma_f32 v[148:149], v[14:15], v[94:95], v[148:149] neg_lo:[1,0,0] neg_hi:[1,0,0]
	ds_read_b128 v[92:95], v195 offset:7392
	s_waitcnt lgkmcnt(4)
	v_pk_fma_f32 v[146:147], v[16:17], v[96:97], v[146:147] neg_lo:[1,0,0] neg_hi:[1,0,0]
	v_pk_fma_f32 v[148:149], v[18:19], v[98:99], v[148:149] neg_lo:[1,0,0] neg_hi:[1,0,0]
	ds_read_b128 v[96:99], v195 offset:7408
	v_pk_fma_f32 v[146:147], v[20:21], v[100:101], v[146:147] neg_lo:[1,0,0] neg_hi:[1,0,0]
	v_pk_fma_f32 v[148:149], v[22:23], v[102:103], v[148:149] neg_lo:[1,0,0] neg_hi:[1,0,0]
	ds_read_b128 v[100:103], v195 offset:7424
	v_pk_fma_f32 v[146:147], v[24:25], v[104:105], v[146:147] neg_lo:[1,0,0] neg_hi:[1,0,0]
	ds_read_b128 v[104:107], v195 offset:7440
	v_add_f32_e32 v150, v147, v146
	v_add_f32_e32 v151, v148, v149
	v_add_f32_e32 v26, v151, v150
	v_cmp_eq_u32_e32 vcc, 27, v188
	s_nop 1
	v_cndmask_b32_e64 v202, 0, 1.0, vcc
	s_waitcnt lgkmcnt(3)
	v_pk_fma_f32 v[146:147], v[0:1], v[80:81], v[202:203] neg_lo:[1,0,0] neg_hi:[1,0,0]
	v_pk_fma_f32 v[148:149], v[2:3], v[82:83], v[200:201] neg_lo:[1,0,0] neg_hi:[1,0,0]
	ds_read_b128 v[80:83], v195 offset:7616
	v_pk_fma_f32 v[146:147], v[4:5], v[84:85], v[146:147] neg_lo:[1,0,0] neg_hi:[1,0,0]
	v_pk_fma_f32 v[148:149], v[6:7], v[86:87], v[148:149] neg_lo:[1,0,0] neg_hi:[1,0,0]
	ds_read_b128 v[84:87], v195 offset:7632
	v_pk_fma_f32 v[146:147], v[8:9], v[88:89], v[146:147] neg_lo:[1,0,0] neg_hi:[1,0,0]
	v_pk_fma_f32 v[148:149], v[10:11], v[90:91], v[148:149] neg_lo:[1,0,0] neg_hi:[1,0,0]
	ds_read_b128 v[88:91], v195 offset:7648
	v_pk_fma_f32 v[146:147], v[12:13], v[92:93], v[146:147] neg_lo:[1,0,0] neg_hi:[1,0,0]
	v_pk_fma_f32 v[148:149], v[14:15], v[94:95], v[148:149] neg_lo:[1,0,0] neg_hi:[1,0,0]
	ds_read_b128 v[92:95], v195 offset:7664
	s_waitcnt lgkmcnt(4)
	v_pk_fma_f32 v[146:147], v[16:17], v[96:97], v[146:147] neg_lo:[1,0,0] neg_hi:[1,0,0]
	v_pk_fma_f32 v[148:149], v[18:19], v[98:99], v[148:149] neg_lo:[1,0,0] neg_hi:[1,0,0]
	ds_read_b128 v[96:99], v195 offset:7680
	v_pk_fma_f32 v[146:147], v[20:21], v[100:101], v[146:147] neg_lo:[1,0,0] neg_hi:[1,0,0]
	v_pk_fma_f32 v[148:149], v[22:23], v[102:103], v[148:149] neg_lo:[1,0,0] neg_hi:[1,0,0]
	ds_read_b128 v[100:103], v195 offset:7696
	v_pk_fma_f32 v[146:147], v[24:25], v[104:105], v[146:147] neg_lo:[1,0,0] neg_hi:[1,0,0]
	v_fma_f32 v148, -v26, v106, v148
	ds_read_b128 v[104:107], v195 offset:7712
	v_add_f32_e32 v150, v147, v146
	v_add_f32_e32 v151, v148, v149
	v_add_f32_e32 v27, v151, v150
	v_cmp_eq_u32_e32 vcc, 28, v188
	s_nop 1
	v_cndmask_b32_e64 v202, 0, 1.0, vcc
	s_waitcnt lgkmcnt(3)
	v_pk_fma_f32 v[146:147], v[0:1], v[80:81], v[202:203] neg_lo:[1,0,0] neg_hi:[1,0,0]
	v_pk_fma_f32 v[148:149], v[2:3], v[82:83], v[200:201] neg_lo:[1,0,0] neg_hi:[1,0,0]
	ds_read_b128 v[80:83], v195 offset:7888
	v_pk_fma_f32 v[146:147], v[4:5], v[84:85], v[146:147] neg_lo:[1,0,0] neg_hi:[1,0,0]
	v_pk_fma_f32 v[148:149], v[6:7], v[86:87], v[148:149] neg_lo:[1,0,0] neg_hi:[1,0,0]
	ds_read_b128 v[84:87], v195 offset:7904
	v_pk_fma_f32 v[146:147], v[8:9], v[88:89], v[146:147] neg_lo:[1,0,0] neg_hi:[1,0,0]
	v_pk_fma_f32 v[148:149], v[10:11], v[90:91], v[148:149] neg_lo:[1,0,0] neg_hi:[1,0,0]
	ds_read_b128 v[88:91], v195 offset:7920
	v_pk_fma_f32 v[146:147], v[12:13], v[92:93], v[146:147] neg_lo:[1,0,0] neg_hi:[1,0,0]
	v_pk_fma_f32 v[148:149], v[14:15], v[94:95], v[148:149] neg_lo:[1,0,0] neg_hi:[1,0,0]
	ds_read_b128 v[92:95], v195 offset:7936
	s_waitcnt lgkmcnt(4)
	v_pk_fma_f32 v[146:147], v[16:17], v[96:97], v[146:147] neg_lo:[1,0,0] neg_hi:[1,0,0]
	v_pk_fma_f32 v[148:149], v[18:19], v[98:99], v[148:149] neg_lo:[1,0,0] neg_hi:[1,0,0]
	ds_read_b128 v[96:99], v195 offset:7952
	v_pk_fma_f32 v[146:147], v[20:21], v[100:101], v[146:147] neg_lo:[1,0,0] neg_hi:[1,0,0]
	v_pk_fma_f32 v[148:149], v[22:23], v[102:103], v[148:149] neg_lo:[1,0,0] neg_hi:[1,0,0]
	ds_read_b128 v[100:103], v195 offset:7968
	v_pk_fma_f32 v[146:147], v[24:25], v[104:105], v[146:147] neg_lo:[1,0,0] neg_hi:[1,0,0]
	v_pk_fma_f32 v[148:149], v[26:27], v[106:107], v[148:149] neg_lo:[1,0,0] neg_hi:[1,0,0]
	ds_read_b128 v[104:107], v195 offset:7984
	ds_read_b128 v[108:111], v195 offset:8000
	v_add_f32_e32 v150, v147, v146
	v_add_f32_e32 v151, v148, v149
	v_add_f32_e32 v28, v151, v150
	v_cmp_eq_u32_e32 vcc, 29, v188
	s_nop 1
	v_cndmask_b32_e64 v202, 0, 1.0, vcc
	s_waitcnt lgkmcnt(4)
	v_pk_fma_f32 v[146:147], v[0:1], v[80:81], v[202:203] neg_lo:[1,0,0] neg_hi:[1,0,0]
	v_pk_fma_f32 v[148:149], v[2:3], v[82:83], v[200:201] neg_lo:[1,0,0] neg_hi:[1,0,0]
	ds_read_b128 v[80:83], v195 offset:8160
	v_pk_fma_f32 v[146:147], v[4:5], v[84:85], v[146:147] neg_lo:[1,0,0] neg_hi:[1,0,0]
	v_pk_fma_f32 v[148:149], v[6:7], v[86:87], v[148:149] neg_lo:[1,0,0] neg_hi:[1,0,0]
	ds_read_b128 v[84:87], v195 offset:8176
	v_pk_fma_f32 v[146:147], v[8:9], v[88:89], v[146:147] neg_lo:[1,0,0] neg_hi:[1,0,0]
	v_pk_fma_f32 v[148:149], v[10:11], v[90:91], v[148:149] neg_lo:[1,0,0] neg_hi:[1,0,0]
	ds_read_b128 v[88:91], v195 offset:8192
	v_pk_fma_f32 v[146:147], v[12:13], v[92:93], v[146:147] neg_lo:[1,0,0] neg_hi:[1,0,0]
	v_pk_fma_f32 v[148:149], v[14:15], v[94:95], v[148:149] neg_lo:[1,0,0] neg_hi:[1,0,0]
	ds_read_b128 v[92:95], v195 offset:8208
	s_waitcnt lgkmcnt(4)
	v_pk_fma_f32 v[146:147], v[16:17], v[96:97], v[146:147] neg_lo:[1,0,0] neg_hi:[1,0,0]
	v_pk_fma_f32 v[148:149], v[18:19], v[98:99], v[148:149] neg_lo:[1,0,0] neg_hi:[1,0,0]
	ds_read_b128 v[96:99], v195 offset:8224
	v_pk_fma_f32 v[146:147], v[20:21], v[100:101], v[146:147] neg_lo:[1,0,0] neg_hi:[1,0,0]
	v_pk_fma_f32 v[148:149], v[22:23], v[102:103], v[148:149] neg_lo:[1,0,0] neg_hi:[1,0,0]
	ds_read_b128 v[100:103], v195 offset:8240
	v_pk_fma_f32 v[146:147], v[24:25], v[104:105], v[146:147] neg_lo:[1,0,0] neg_hi:[1,0,0]
	v_pk_fma_f32 v[148:149], v[26:27], v[106:107], v[148:149] neg_lo:[1,0,0] neg_hi:[1,0,0]
	ds_read_b128 v[104:107], v195 offset:8256
	v_fma_f32 v146, -v28, v108, v146
	ds_read_b128 v[108:111], v195 offset:8272
	v_add_f32_e32 v150, v147, v146
	v_add_f32_e32 v151, v148, v149
	v_add_f32_e32 v29, v151, v150
	v_cmp_eq_u32_e32 vcc, 30, v188
	s_nop 1
	v_cndmask_b32_e64 v202, 0, 1.0, vcc
	s_waitcnt lgkmcnt(4)
	v_pk_fma_f32 v[146:147], v[0:1], v[80:81], v[202:203] neg_lo:[1,0,0] neg_hi:[1,0,0]
	v_pk_fma_f32 v[148:149], v[2:3], v[82:83], v[200:201] neg_lo:[1,0,0] neg_hi:[1,0,0]
	ds_read_b128 v[80:83], v195 offset:8432
	v_pk_fma_f32 v[146:147], v[4:5], v[84:85], v[146:147] neg_lo:[1,0,0] neg_hi:[1,0,0]
	v_pk_fma_f32 v[148:149], v[6:7], v[86:87], v[148:149] neg_lo:[1,0,0] neg_hi:[1,0,0]
	ds_read_b128 v[84:87], v195 offset:8448
	v_pk_fma_f32 v[146:147], v[8:9], v[88:89], v[146:147] neg_lo:[1,0,0] neg_hi:[1,0,0]
	v_pk_fma_f32 v[148:149], v[10:11], v[90:91], v[148:149] neg_lo:[1,0,0] neg_hi:[1,0,0]
	ds_read_b128 v[88:91], v195 offset:8464
	v_pk_fma_f32 v[146:147], v[12:13], v[92:93], v[146:147] neg_lo:[1,0,0] neg_hi:[1,0,0]
	v_pk_fma_f32 v[148:149], v[14:15], v[94:95], v[148:149] neg_lo:[1,0,0] neg_hi:[1,0,0]
	ds_read_b128 v[92:95], v195 offset:8480
	s_waitcnt lgkmcnt(4)
	v_pk_fma_f32 v[146:147], v[16:17], v[96:97], v[146:147] neg_lo:[1,0,0] neg_hi:[1,0,0]
	v_pk_fma_f32 v[148:149], v[18:19], v[98:99], v[148:149] neg_lo:[1,0,0] neg_hi:[1,0,0]
	ds_read_b128 v[96:99], v195 offset:8496
	v_pk_fma_f32 v[146:147], v[20:21], v[100:101], v[146:147] neg_lo:[1,0,0] neg_hi:[1,0,0]
	v_pk_fma_f32 v[148:149], v[22:23], v[102:103], v[148:149] neg_lo:[1,0,0] neg_hi:[1,0,0]
	ds_read_b128 v[100:103], v195 offset:8512
	v_pk_fma_f32 v[146:147], v[24:25], v[104:105], v[146:147] neg_lo:[1,0,0] neg_hi:[1,0,0]
	v_pk_fma_f32 v[148:149], v[26:27], v[106:107], v[148:149] neg_lo:[1,0,0] neg_hi:[1,0,0]
	ds_read_b128 v[104:107], v195 offset:8528
	v_pk_fma_f32 v[146:147], v[28:29], v[108:109], v[146:147] neg_lo:[1,0,0] neg_hi:[1,0,0]
	ds_read_b128 v[108:111], v195 offset:8544
	v_add_f32_e32 v150, v147, v146
	v_add_f32_e32 v151, v148, v149
	v_add_f32_e32 v30, v151, v150
	v_cmp_eq_u32_e32 vcc, 31, v188
	s_nop 1
	v_cndmask_b32_e64 v202, 0, 1.0, vcc
	s_waitcnt lgkmcnt(4)
	v_pk_fma_f32 v[146:147], v[0:1], v[80:81], v[202:203] neg_lo:[1,0,0] neg_hi:[1,0,0]
	v_pk_fma_f32 v[148:149], v[2:3], v[82:83], v[200:201] neg_lo:[1,0,0] neg_hi:[1,0,0]
	v_pk_fma_f32 v[146:147], v[4:5], v[84:85], v[146:147] neg_lo:[1,0,0] neg_hi:[1,0,0]
	v_pk_fma_f32 v[148:149], v[6:7], v[86:87], v[148:149] neg_lo:[1,0,0] neg_hi:[1,0,0]
	v_pk_fma_f32 v[146:147], v[8:9], v[88:89], v[146:147] neg_lo:[1,0,0] neg_hi:[1,0,0]
	v_pk_fma_f32 v[148:149], v[10:11], v[90:91], v[148:149] neg_lo:[1,0,0] neg_hi:[1,0,0]
	v_pk_fma_f32 v[146:147], v[12:13], v[92:93], v[146:147] neg_lo:[1,0,0] neg_hi:[1,0,0]
	v_pk_fma_f32 v[148:149], v[14:15], v[94:95], v[148:149] neg_lo:[1,0,0] neg_hi:[1,0,0]
	s_waitcnt lgkmcnt(0)
	v_pk_fma_f32 v[146:147], v[16:17], v[96:97], v[146:147] neg_lo:[1,0,0] neg_hi:[1,0,0]
	v_pk_fma_f32 v[148:149], v[18:19], v[98:99], v[148:149] neg_lo:[1,0,0] neg_hi:[1,0,0]
	v_pk_fma_f32 v[146:147], v[20:21], v[100:101], v[146:147] neg_lo:[1,0,0] neg_hi:[1,0,0]
	v_pk_fma_f32 v[148:149], v[22:23], v[102:103], v[148:149] neg_lo:[1,0,0] neg_hi:[1,0,0]
	v_pk_fma_f32 v[146:147], v[24:25], v[104:105], v[146:147] neg_lo:[1,0,0] neg_hi:[1,0,0]
	v_pk_fma_f32 v[148:149], v[26:27], v[106:107], v[148:149] neg_lo:[1,0,0] neg_hi:[1,0,0]
	v_pk_fma_f32 v[146:147], v[28:29], v[108:109], v[146:147] neg_lo:[1,0,0] neg_hi:[1,0,0]
	v_fma_f32 v148, -v30, v110, v148
	v_add_f32_e32 v150, v147, v146
	v_add_f32_e32 v151, v148, v149
	v_add_f32_e32 v31, v151, v150
	v_mul_u32_u24_e32 v204, 0x110, v188
	v_lshl_add_u32 v204, v189, 2, v204
	v_add_u32_e32 v204, 0x2200, v204
	v_add_u32_e32 v196, v194, v204
	v_mul_u32_u24_e32 v204, 132, v188
	v_lshl_add_u32 v204, v189, 2, v204
	v_add_u32_e32 v197, s0, v204
	v_mul_u32_u24_e32 v204, 132, v189
	v_add3_u32 v198, v204, v199, s0
	s_nop 1
	v_permlane32_swap_b32_e32 v0, v1
	v_permlane32_swap_b32_e32 v2, v3
	v_permlane32_swap_b32_e32 v4, v5
	v_permlane32_swap_b32_e32 v6, v7
	v_permlane32_swap_b32_e32 v8, v9
	v_permlane32_swap_b32_e32 v10, v11
	v_permlane32_swap_b32_e32 v12, v13
	v_permlane32_swap_b32_e32 v14, v15
	v_permlane32_swap_b32_e32 v16, v17
	v_permlane32_swap_b32_e32 v18, v19
	v_permlane32_swap_b32_e32 v20, v21
	v_permlane32_swap_b32_e32 v22, v23
	v_permlane32_swap_b32_e32 v24, v25
	v_permlane32_swap_b32_e32 v26, v27
	v_permlane32_swap_b32_e32 v28, v29
	v_permlane32_swap_b32_e32 v30, v31
	ds_read2_b32 v[32:33], v196 offset0:0 offset1:2
	ds_read2_b32 v[34:35], v196 offset0:4 offset1:6
	ds_read2_b32 v[36:37], v196 offset0:8 offset1:10
	ds_read2_b32 v[38:39], v196 offset0:12 offset1:14
	ds_read2_b32 v[40:41], v196 offset0:16 offset1:18
	ds_read2_b32 v[42:43], v196 offset0:20 offset1:22
	ds_read2_b32 v[44:45], v196 offset0:24 offset1:26
	ds_read2_b32 v[46:47], v196 offset0:28 offset1:30
	v_xor_b32_e32 v204, 0x80000000, v1
	ds_write_b32 v198, v204
	v_xor_b32_e32 v205, 0x80000000, v3
	ds_write_b32 v198, v205 offset:264
	v_xor_b32_e32 v204, 0x80000000, v5
	ds_write_b32 v198, v204 offset:528
	v_xor_b32_e32 v205, 0x80000000, v7
	ds_write_b32 v198, v205 offset:792
	v_xor_b32_e32 v204, 0x80000000, v9
	ds_write_b32 v198, v204 offset:1056
	v_xor_b32_e32 v205, 0x80000000, v11
	ds_write_b32 v198, v205 offset:1320
	v_xor_b32_e32 v204, 0x80000000, v13
	ds_write_b32 v198, v204 offset:1584
	v_xor_b32_e32 v205, 0x80000000, v15
	s_waitcnt lgkmcnt(14)
	ds_write_b32 v198, v205 offset:1848
	v_xor_b32_e32 v204, 0x80000000, v17
	s_waitcnt lgkmcnt(14)
	ds_write_b32 v198, v204 offset:2112
	v_xor_b32_e32 v205, 0x80000000, v19
	s_waitcnt lgkmcnt(14)
	ds_write_b32 v198, v205 offset:2376
	v_xor_b32_e32 v204, 0x80000000, v21
	s_waitcnt lgkmcnt(14)
	ds_write_b32 v198, v204 offset:2640
	v_xor_b32_e32 v205, 0x80000000, v23
	s_waitcnt lgkmcnt(14)
	ds_write_b32 v198, v205 offset:2904
	v_xor_b32_e32 v204, 0x80000000, v25
	s_waitcnt lgkmcnt(14)
	ds_write_b32 v198, v204 offset:3168
	v_xor_b32_e32 v205, 0x80000000, v27
	s_waitcnt lgkmcnt(14)
	ds_write_b32 v198, v205 offset:3432
	v_xor_b32_e32 v204, 0x80000000, v29
	s_waitcnt lgkmcnt(14)
	ds_write_b32 v198, v204 offset:3696
	v_xor_b32_e32 v205, 0x80000000, v31
	s_waitcnt lgkmcnt(14)
	ds_write_b32 v198, v205 offset:3960
	s_waitcnt lgkmcnt(14)
	ds_read2_b32 v[48:49], v197 offset0:0 offset1:2
	s_waitcnt lgkmcnt(14)
	ds_read2_b32 v[50:51], v197 offset0:4 offset1:6
	s_waitcnt lgkmcnt(14)
	ds_read2_b32 v[52:53], v197 offset0:8 offset1:10
	s_waitcnt lgkmcnt(14)
	ds_read2_b32 v[54:55], v197 offset0:12 offset1:14
	s_waitcnt lgkmcnt(14)
	ds_read2_b32 v[56:57], v197 offset0:16 offset1:18
	s_waitcnt lgkmcnt(14)
	ds_read2_b32 v[58:59], v197 offset0:20 offset1:22
	s_waitcnt lgkmcnt(14)
	ds_read2_b32 v[60:61], v197 offset0:24 offset1:26
	s_waitcnt lgkmcnt(14)
	ds_read2_b32 v[62:63], v197 offset0:28 offset1:30
	v_mfma_f32_32x32x2_f32 v[64:79], v32, v0, 0
	v_mfma_f32_32x32x2_f32 v[64:79], v33, v2, v[64:79]
	v_mfma_f32_32x32x2_f32 v[64:79], v34, v4, v[64:79]
	v_mfma_f32_32x32x2_f32 v[64:79], v35, v6, v[64:79]
	v_mfma_f32_32x32x2_f32 v[64:79], v36, v8, v[64:79]
	v_mfma_f32_32x32x2_f32 v[64:79], v37, v10, v[64:79]
	v_mfma_f32_32x32x2_f32 v[64:79], v38, v12, v[64:79]
	v_mfma_f32_32x32x2_f32 v[64:79], v39, v14, v[64:79]
	v_mfma_f32_32x32x2_f32 v[64:79], v40, v16, v[64:79]
	v_mfma_f32_32x32x2_f32 v[64:79], v41, v18, v[64:79]
	v_mfma_f32_32x32x2_f32 v[64:79], v42, v20, v[64:79]
	v_mfma_f32_32x32x2_f32 v[64:79], v43, v22, v[64:79]
	v_mfma_f32_32x32x2_f32 v[64:79], v44, v24, v[64:79]
	v_mfma_f32_32x32x2_f32 v[64:79], v45, v26, v[64:79]
	v_mfma_f32_32x32x2_f32 v[64:79], v46, v28, v[64:79]
	v_mfma_f32_32x32x2_f32 v[64:79], v47, v30, v[64:79]
	s_cmp_lg_u32 s87, 0
	s_cbranch_scc1 .Ltri3_dg_b
	v_mul_u32_u24_e32 v204, 0x110, v189
	v_add3_u32 v204, v204, v199, v194
	ds_write_b32 v204, v0
	ds_write_b32 v204, v1 offset:8832
	ds_write_b32 v204, v2 offset:544
	ds_write_b32 v204, v3 offset:9376
	ds_write_b32 v204, v4 offset:1088
	ds_write_b32 v204, v5 offset:9920
	ds_write_b32 v204, v6 offset:1632
	ds_write_b32 v204, v7 offset:10464
	ds_write_b32 v204, v8 offset:2176
	ds_write_b32 v204, v9 offset:11008
	ds_write_b32 v204, v10 offset:2720
	ds_write_b32 v204, v11 offset:11552
	ds_write_b32 v204, v12 offset:3264
	ds_write_b32 v204, v13 offset:12096
	ds_write_b32 v204, v14 offset:3808
	ds_write_b32 v204, v15 offset:12640
	ds_write_b32 v204, v16 offset:4352
	ds_write_b32 v204, v17 offset:13184
	ds_write_b32 v204, v18 offset:4896
	ds_write_b32 v204, v19 offset:13728
	ds_write_b32 v204, v20 offset:5440
	ds_write_b32 v204, v21 offset:14272
	ds_write_b32 v204, v22 offset:5984
	ds_write_b32 v204, v23 offset:14816
	ds_write_b32 v204, v24 offset:6528
	ds_write_b32 v204, v25 offset:15360
	ds_write_b32 v204, v26 offset:7072
	ds_write_b32 v204, v27 offset:15904
	ds_write_b32 v204, v28 offset:7616
	ds_write_b32 v204, v29 offset:16448
	ds_write_b32 v204, v30 offset:8160
	ds_write_b32 v204, v31 offset:16992
	s_branch .Ltri3_dg_done
.Ltri3_dg_b:
	v_sub_u32_e32 v150, 33, v189
	v_mul_u32_u24_e32 v150, 0x110, v150
	v_sub_u32_e32 v151, 63, v188
	v_lshl_add_u32 v150, v151, 2, v150
	v_add_u32_e32 v204, v194, v150
	v_add_u32_e32 v205, 0xffffdd80, v204
	ds_write_b32 v204, v0 offset:8160
	ds_write_b32 v205, v1 offset:8160
	ds_write_b32 v204, v2 offset:7616
	ds_write_b32 v205, v3 offset:7616
	ds_write_b32 v204, v4 offset:7072
	ds_write_b32 v205, v5 offset:7072
	ds_write_b32 v204, v6 offset:6528
	ds_write_b32 v205, v7 offset:6528
	ds_write_b32 v204, v8 offset:5984
	ds_write_b32 v205, v9 offset:5984
	ds_write_b32 v204, v10 offset:5440
	ds_write_b32 v205, v11 offset:5440
	ds_write_b32 v204, v12 offset:4896
	ds_write_b32 v205, v13 offset:4896
	ds_write_b32 v204, v14 offset:4352
	ds_write_b32 v205, v15 offset:4352
	ds_write_b32 v204, v16 offset:3808
	ds_write_b32 v205, v17 offset:3808
	ds_write_b32 v204, v18 offset:3264
	ds_write_b32 v205, v19 offset:3264
	ds_write_b32 v204, v20 offset:2720
	ds_write_b32 v205, v21 offset:2720
	ds_write_b32 v204, v22 offset:2176
	ds_write_b32 v205, v23 offset:2176
	ds_write_b32 v204, v24 offset:1632
	ds_write_b32 v205, v25 offset:1632
	ds_write_b32 v204, v26 offset:1088
	ds_write_b32 v205, v27 offset:1088
	ds_write_b32 v204, v28 offset:544
	ds_write_b32 v205, v29 offset:544
	ds_write_b32 v204, v30
	ds_write_b32 v205, v31
.Ltri3_dg_done:
	s_waitcnt lgkmcnt(0)
	s_nop 7
	s_nop 7
	s_nop 3
	v_permlane32_swap_b32_e32 v64, v65
	v_permlane32_swap_b32_e32 v66, v67
	v_permlane32_swap_b32_e32 v68, v69
	v_permlane32_swap_b32_e32 v70, v71
	v_permlane32_swap_b32_e32 v72, v73
	v_permlane32_swap_b32_e32 v74, v75
	v_permlane32_swap_b32_e32 v76, v77
	v_permlane32_swap_b32_e32 v78, v79
	s_nop 1
	v_mfma_f32_32x32x2_f32 v[170:185], v48, v64, 0
	v_mfma_f32_32x32x2_f32 v[170:185], v49, v66, v[170:185]
	v_mfma_f32_32x32x2_f32 v[170:185], v50, v65, v[170:185]
	v_mfma_f32_32x32x2_f32 v[170:185], v51, v67, v[170:185]
	v_mfma_f32_32x32x2_f32 v[170:185], v52, v68, v[170:185]
	v_mfma_f32_32x32x2_f32 v[170:185], v53, v70, v[170:185]
	v_mfma_f32_32x32x2_f32 v[170:185], v54, v69, v[170:185]
	v_mfma_f32_32x32x2_f32 v[170:185], v55, v71, v[170:185]
	v_mfma_f32_32x32x2_f32 v[170:185], v56, v72, v[170:185]
	v_mfma_f32_32x32x2_f32 v[170:185], v57, v74, v[170:185]
	v_mfma_f32_32x32x2_f32 v[170:185], v58, v73, v[170:185]
	v_mfma_f32_32x32x2_f32 v[170:185], v59, v75, v[170:185]
	v_mfma_f32_32x32x2_f32 v[170:185], v60, v76, v[170:185]
	v_mfma_f32_32x32x2_f32 v[170:185], v61, v78, v[170:185]
	v_mfma_f32_32x32x2_f32 v[170:185], v62, v77, v[170:185]
	v_mfma_f32_32x32x2_f32 v[170:185], v63, v79, v[170:185]
	s_nop 7
	s_nop 7
	s_nop 3
	s_cmp_lg_u32 s87, 0
	s_cbranch_scc1 .Ltri2_wb_b
	v_mul_u32_u24_e32 v204, 0x440, v189
	v_add3_u32 v204, v204, v199, v194
	v_add_u32_e32 v204, 0x2200, v204
	ds_write_b32 v204, v170
	ds_write_b32 v204, v171 offset:272
	ds_write_b32 v204, v172 offset:544
	ds_write_b32 v204, v173 offset:816
	ds_write_b32 v204, v174 offset:2176
	ds_write_b32 v204, v175 offset:2448
	ds_write_b32 v204, v176 offset:2720
	ds_write_b32 v204, v177 offset:2992
	ds_write_b32 v204, v178 offset:4352
	ds_write_b32 v204, v179 offset:4624
	ds_write_b32 v204, v180 offset:4896
	ds_write_b32 v204, v181 offset:5168
	ds_write_b32 v204, v182 offset:6528
	ds_write_b32 v204, v183 offset:6800
	ds_write_b32 v204, v184 offset:7072
	ds_write_b32 v204, v185 offset:7344
	s_branch .Ltri2_wb_done
.Ltri2_wb_b:
	v_sub_u32_e32 v150, 1, v189
	v_mul_u32_u24_e32 v150, 0x440, v150
	v_sub_u32_e32 v151, 63, v188
	v_lshl_add_u32 v150, v151, 2, v150
	v_add_u32_e32 v204, v194, v150
	ds_write_b32 v204, v170 offset:7344
	ds_write_b32 v204, v171 offset:7072
	ds_write_b32 v204, v172 offset:6800
	ds_write_b32 v204, v173 offset:6528
	ds_write_b32 v204, v174 offset:5168
	ds_write_b32 v204, v175 offset:4896
	ds_write_b32 v204, v176 offset:4624
	ds_write_b32 v204, v177 offset:4352
	ds_write_b32 v204, v178 offset:2992
	ds_write_b32 v204, v179 offset:2720
	ds_write_b32 v204, v180 offset:2448
	ds_write_b32 v204, v181 offset:2176
	ds_write_b32 v204, v182 offset:816
	ds_write_b32 v204, v183 offset:544
	ds_write_b32 v204, v184 offset:272
	ds_write_b32 v204, v185
	v_sub_u32_e32 v150, 1, v189
	v_mul_u32_u24_e32 v151, 0x1100, v150
	v_sub_u32_e32 v153, 31, v188
	v_lshlrev_b32_e32 v153, 2, v153
	v_add_u32_e32 v151, 0x2200, v151
	v_add3_u32 v204, v194, v151, v153
	ds_write_b32 v204, v200 offset:4080
	ds_write_b32 v204, v200 offset:3808
	ds_write_b32 v204, v200 offset:3536
	ds_write_b32 v204, v200 offset:3264
	ds_write_b32 v204, v200 offset:2992
	ds_write_b32 v204, v200 offset:2720
	ds_write_b32 v204, v200 offset:2448
	ds_write_b32 v204, v200 offset:2176
	ds_write_b32 v204, v200 offset:1904
	ds_write_b32 v204, v200 offset:1632
	ds_write_b32 v204, v200 offset:1360
	ds_write_b32 v204, v200 offset:1088
	ds_write_b32 v204, v200 offset:816
	ds_write_b32 v204, v200 offset:544
	ds_write_b32 v204, v200 offset:272
	ds_write_b32 v204, v200
